# EpiMerge epilogue: gate/t1 loads prefetched in batches of 8 with counted vmcnt (on top of GLA prefetch restructure)
# speedup vs baseline: 1.0021x; 1.0021x over previous
; __device__ __forceinline__ float bflo(unsigned w) { return __uint_as_float(w << 16); }
; __device__ __forceinline__ float bfhi(unsigned w) { return __uint_as_float(w & 0xffff0000u); }
;     __device__ __forceinline__ void operator()(const f32x4 (&acc)[2][2][4][2], const Unit& u, int wr, int wc, int fr, int fq, const LAS float* rsl) const {
;         const int row0 = u.pm * 256 + wr * 64 + fr;
; #pragma unroll
;         for (int ai = 0; ai < 2; ++ai)
; #pragma unroll
;             for (int m = 0; m < 4; ++m) {
;                 const int row = row0 + ai * 128 + m * 16;
; #pragma unroll
;                 for (int bj = 0; bj < 2; ++bj) {
;                     bf16_t* ptr = P + (size_t)row * PW + u.pn * 256 + bj * 128 + wc * 32 + 8 * fq;
;                     const u32x4 g = *(const u32x4*)ptr; const u32x4 t = *(const u32x4*)(ptr + 1024);
;                     f32x4 v0 = acc[ai][bj][m][0], v1 = acc[ai][bj][m][1];
;                     v0[0] = v0[0] * bflo(g.x) + bflo(t.x); v0[1] = v0[1] * bfhi(g.x) + bfhi(t.x); v0[2] = v0[2] * bflo(g.y) + bflo(t.y); v0[3] = v0[3] * bfhi(g.y) + bfhi(t.y);
;                     v1[0] = v1[0] * bflo(g.z) + bflo(t.z); v1[1] = v1[1] * bfhi(g.z) + bfhi(t.z); v1[2] = v1[2] * bflo(g.w) + bflo(t.w); v1[3] = v1[3] * bfhi(g.w) + bfhi(t.w);
;                     *(u32x4*)ptr = pack8(v0, v1);
;                 }
.LBB0_317:
	s_lshl_b32 s0, s47, 8
	v_lshl_add_u32 v157, s46, 8, v142
	s_ashr_i32 s1, s0, 31
	v_mov_b64_e32 v[140:141], s[72:73]
	v_mad_i64_i32 v[158:159], s[2:3], v157, s80, v[140:141]
	s_lshl_b64 s[0:1], s[0:1], 1
	v_lshl_add_u64 v[158:159], v[158:159], 0, s[0:1]
	v_lshl_add_u64 v[158:159], v[158:159], 0, s[68:69]
	v_lshl_add_u64 v[166:167], v[158:159], 0, v[146:147]
	v_mbcnt_lo_u32_b32 v159, -1, 0
	v_mbcnt_hi_u32_b32 v159, -1, v159
	v_and_b32_e32 v158, 15, v159
	v_lshrrev_b32_e32 v159, 4, v159
	v_mul_u32_u24_e32 v158, 0x1c00, v158
	v_readfirstlane_b32 s2, v166
	v_readfirstlane_b32 s3, v167
	v_lshl_or_b32 v158, v159, 4, v158
	s_nop 4
	global_load_dwordx4 v[172:175], v158, s[2:3]
	global_load_dwordx4 v[176:179], v158, s[2:3] offset:2048
	global_load_dwordx4 v[180:183], v158, s[2:3] offset:256
	global_load_dwordx4 v[184:187], v158, s[2:3] offset:2304
	s_add_u32 s2, s2, 0x1c000
	s_addc_u32 s3, s3, 0
	global_load_dwordx4 v[188:191], v158, s[2:3]
	global_load_dwordx4 v[192:195], v158, s[2:3] offset:2048
	global_load_dwordx4 v[196:199], v158, s[2:3] offset:256
	global_load_dwordx4 v[200:203], v158, s[2:3] offset:2304
	s_waitcnt vmcnt(6)
	s_nop 1
	v_mov_b32_e32 v158, v172
	v_mov_b32_e32 v159, v173
	v_mov_b32_e32 v160, v174
	v_mov_b32_e32 v161, v175
	v_mov_b32_e32 v162, v176
	v_mov_b32_e32 v163, v177
	v_mov_b32_e32 v164, v178
	v_mov_b32_e32 v165, v179
	s_and_b64 vcc, exec, s[10:11]
	v_lshlrev_b32_e32 v168, 16, v158
	v_and_b32_e32 v169, 0xffff0000, v158
	v_lshlrev_b32_e32 v170, 16, v162
	v_and_b32_e32 v171, 0xffff0000, v162
	v_lshlrev_b32_e32 v158, 16, v159
	v_and_b32_e32 v159, 0xffff0000, v159
	v_lshlrev_b32_e32 v162, 16, v163
	v_and_b32_e32 v163, 0xffff0000, v163
	v_pk_fma_f32 v[126:127], v[126:127], v[158:159], v[162:163]
	v_lshlrev_b32_e32 v158, 16, v160
	v_and_b32_e32 v159, 0xffff0000, v160
	v_lshlrev_b32_e32 v162, 16, v164
	v_and_b32_e32 v163, 0xffff0000, v164
	v_pk_fma_f32 v[158:159], v[120:121], v[158:159], v[162:163]
	v_lshlrev_b32_e32 v120, 16, v161
	v_and_b32_e32 v121, 0xffff0000, v161
	v_lshlrev_b32_e32 v160, 16, v165
	v_and_b32_e32 v161, 0xffff0000, v165
	v_pk_fma_f32 v[124:125], v[124:125], v[168:169], v[170:171]
	v_pk_fma_f32 v[160:161], v[122:123], v[120:121], v[160:161]
	v_cvt_pk_bf16_f32 v120, v124, v125
	v_cvt_pk_bf16_f32 v121, v126, v127
	v_cvt_pk_bf16_f32 v122, v158, v159
	v_cvt_pk_bf16_f32 v123, v160, v161
	global_store_dwordx4 v[166:167], v[120:123], off
	s_waitcnt vmcnt(5)
	s_nop 1
	v_mov_b32_e32 v120, v180
	v_mov_b32_e32 v121, v181
	v_mov_b32_e32 v122, v182
	v_mov_b32_e32 v123, v183
	s_nop 0
	v_mov_b32_e32 v124, v184
	v_mov_b32_e32 v125, v185
	v_mov_b32_e32 v126, v186
	v_mov_b32_e32 v127, v187
	v_lshlrev_b32_e32 v158, 16, v120
	v_and_b32_e32 v159, 0xffff0000, v120
	v_lshlrev_b32_e32 v160, 16, v124
	v_and_b32_e32 v161, 0xffff0000, v124
	v_lshlrev_b32_e32 v120, 16, v121
	v_and_b32_e32 v121, 0xffff0000, v121
	v_lshlrev_b32_e32 v124, 16, v125
	v_and_b32_e32 v125, 0xffff0000, v125
	v_pk_fma_f32 v[118:119], v[118:119], v[120:121], v[124:125]
	v_lshlrev_b32_e32 v120, 16, v122
	v_and_b32_e32 v121, 0xffff0000, v122
	v_lshlrev_b32_e32 v124, 16, v126
	v_and_b32_e32 v125, 0xffff0000, v126
	v_pk_fma_f32 v[120:121], v[112:113], v[120:121], v[124:125]
	v_lshlrev_b32_e32 v112, 16, v123
	v_and_b32_e32 v113, 0xffff0000, v123
	v_lshlrev_b32_e32 v122, 16, v127
	v_and_b32_e32 v123, 0xffff0000, v127
	v_pk_fma_f32 v[116:117], v[116:117], v[158:159], v[160:161]
	v_pk_fma_f32 v[122:123], v[114:115], v[112:113], v[122:123]
	v_cvt_pk_bf16_f32 v112, v116, v117
	v_cvt_pk_bf16_f32 v113, v118, v119
	v_cvt_pk_bf16_f32 v114, v120, v121
	v_cvt_pk_bf16_f32 v115, v122, v123
	global_store_dwordx4 v[166:167], v[112:115], off offset:256
	s_nop 1
	v_or_b32_e32 v112, 16, v157
	v_mad_i64_i32 v[112:113], s[2:3], v112, s80, v[140:141]
	v_lshl_add_u64 v[112:113], v[112:113], 0, s[0:1]
	v_lshl_add_u64 v[112:113], v[112:113], 0, s[68:69]
	v_lshl_add_u64 v[112:113], v[112:113], 0, v[146:147]
	s_waitcnt vmcnt(4)
	s_nop 1
	v_mov_b32_e32 v114, v188
	v_mov_b32_e32 v115, v189
	v_mov_b32_e32 v116, v190
	v_mov_b32_e32 v117, v191
	v_mov_b32_e32 v118, v192
	v_mov_b32_e32 v119, v193
	v_mov_b32_e32 v120, v194
	v_mov_b32_e32 v121, v195
	v_lshlrev_b32_e32 v122, 16, v114
	v_and_b32_e32 v123, 0xffff0000, v114
	v_lshlrev_b32_e32 v124, 16, v118
	v_and_b32_e32 v125, 0xffff0000, v118
	v_lshlrev_b32_e32 v114, 16, v115
	v_and_b32_e32 v115, 0xffff0000, v115
	v_lshlrev_b32_e32 v118, 16, v119
	v_and_b32_e32 v119, 0xffff0000, v119
	v_pk_fma_f32 v[110:111], v[110:111], v[114:115], v[118:119]
	v_lshlrev_b32_e32 v114, 16, v116
	v_and_b32_e32 v115, 0xffff0000, v116
	v_lshlrev_b32_e32 v118, 16, v120
	v_and_b32_e32 v119, 0xffff0000, v120
	v_pk_fma_f32 v[114:115], v[104:105], v[114:115], v[118:119]
	v_lshlrev_b32_e32 v104, 16, v117
	v_and_b32_e32 v105, 0xffff0000, v117
	v_lshlrev_b32_e32 v116, 16, v121
	v_and_b32_e32 v117, 0xffff0000, v121
	v_pk_fma_f32 v[108:109], v[108:109], v[122:123], v[124:125]
	v_pk_fma_f32 v[116:117], v[106:107], v[104:105], v[116:117]
	v_cvt_pk_bf16_f32 v104, v108, v109
	v_cvt_pk_bf16_f32 v105, v110, v111
	v_cvt_pk_bf16_f32 v106, v114, v115
	v_cvt_pk_bf16_f32 v107, v116, v117
	global_store_dwordx4 v[112:113], v[104:107], off
	s_waitcnt vmcnt(3)
; __device__ __forceinline__ float bflo(unsigned w) { return __uint_as_float(w << 16); }
; __device__ __forceinline__ float bfhi(unsigned w) { return __uint_as_float(w & 0xffff0000u); }
;     __device__ __forceinline__ void operator()(const f32x4 (&acc)[2][2][4][2], const Unit& u, int wr, int wc, int fr, int fq, const LAS float* rsl) const {
;     ...
;                 const int row = row0 + ai * 128 + m * 16;
; #pragma unroll
;                 for (int bj = 0; bj < 2; ++bj) {
;                     bf16_t* ptr = P + (size_t)row * PW + u.pn * 256 + bj * 128 + wc * 32 + 8 * fq;
;                     const u32x4 g = *(const u32x4*)ptr; const u32x4 t = *(const u32x4*)(ptr + 1024);
;                     f32x4 v0 = acc[ai][bj][m][0], v1 = acc[ai][bj][m][1];
;                     v0[0] = v0[0] * bflo(g.x) + bflo(t.x); v0[1] = v0[1] * bfhi(g.x) + bfhi(t.x); v0[2] = v0[2] * bflo(g.y) + bflo(t.y); v0[3] = v0[3] * bfhi(g.y) + bfhi(t.y);
;                     v1[0] = v1[0] * bflo(g.z) + bflo(t.z); v1[1] = v1[1] * bfhi(g.z) + bfhi(t.z); v1[2] = v1[2] * bflo(g.w) + bflo(t.w); v1[3] = v1[3] * bfhi(g.w) + bfhi(t.w);
;                     *(u32x4*)ptr = pack8(v0, v1);
;                 }
	s_nop 1
	v_mov_b32_e32 v104, v196
	v_mov_b32_e32 v105, v197
	v_mov_b32_e32 v106, v198
	v_mov_b32_e32 v107, v199
	s_nop 0
	v_mov_b32_e32 v108, v200
	v_mov_b32_e32 v109, v201
	v_mov_b32_e32 v110, v202
	v_mov_b32_e32 v111, v203
	v_lshlrev_b32_e32 v114, 16, v104
	v_and_b32_e32 v115, 0xffff0000, v104
	v_lshlrev_b32_e32 v116, 16, v108
	v_and_b32_e32 v117, 0xffff0000, v108
	v_lshlrev_b32_e32 v104, 16, v105
	v_and_b32_e32 v105, 0xffff0000, v105
	v_lshlrev_b32_e32 v108, 16, v109
	v_and_b32_e32 v109, 0xffff0000, v109
	v_pk_fma_f32 v[102:103], v[102:103], v[104:105], v[108:109]
	v_lshlrev_b32_e32 v104, 16, v106
	v_and_b32_e32 v105, 0xffff0000, v106
	v_lshlrev_b32_e32 v108, 16, v110
	v_and_b32_e32 v109, 0xffff0000, v110
	v_pk_fma_f32 v[104:105], v[96:97], v[104:105], v[108:109]
	v_lshlrev_b32_e32 v96, 16, v107
	v_and_b32_e32 v97, 0xffff0000, v107
	v_lshlrev_b32_e32 v106, 16, v111
	v_and_b32_e32 v107, 0xffff0000, v111
	v_pk_fma_f32 v[100:101], v[100:101], v[114:115], v[116:117]
	v_pk_fma_f32 v[106:107], v[98:99], v[96:97], v[106:107]
	v_cvt_pk_bf16_f32 v96, v100, v101
	v_cvt_pk_bf16_f32 v97, v102, v103
	v_cvt_pk_bf16_f32 v98, v104, v105
	v_cvt_pk_bf16_f32 v99, v106, v107
	global_store_dwordx4 v[112:113], v[96:99], off offset:256
	s_nop 1
	v_or_b32_e32 v96, 32, v157
	v_mad_i64_i32 v[96:97], s[2:3], v96, s80, v[140:141]
	v_lshl_add_u64 v[96:97], v[96:97], 0, s[0:1]
	v_lshl_add_u64 v[96:97], v[96:97], 0, s[68:69]
	v_lshl_add_u64 v[96:97], v[96:97], 0, v[146:147]
	v_mbcnt_lo_u32_b32 v99, -1, 0
	v_mbcnt_hi_u32_b32 v99, -1, v99
	v_and_b32_e32 v98, 15, v99
	v_lshrrev_b32_e32 v99, 4, v99
	v_mul_u32_u24_e32 v98, 0x1c00, v98
	v_readfirstlane_b32 s2, v96
	v_readfirstlane_b32 s3, v97
	v_lshl_or_b32 v98, v99, 4, v98
	s_nop 4
	global_load_dwordx4 v[172:175], v98, s[2:3]
	global_load_dwordx4 v[176:179], v98, s[2:3] offset:2048
	global_load_dwordx4 v[180:183], v98, s[2:3] offset:256
	global_load_dwordx4 v[184:187], v98, s[2:3] offset:2304
	s_add_u32 s2, s2, 0x1c000
	s_addc_u32 s3, s3, 0
	global_load_dwordx4 v[188:191], v98, s[2:3]
	global_load_dwordx4 v[192:195], v98, s[2:3] offset:2048
	global_load_dwordx4 v[196:199], v98, s[2:3] offset:256
	global_load_dwordx4 v[200:203], v98, s[2:3] offset:2304
	s_waitcnt vmcnt(6)
	s_nop 1
	v_mov_b32_e32 v98, v172
	v_mov_b32_e32 v99, v173
	v_mov_b32_e32 v100, v174
	v_mov_b32_e32 v101, v175
	v_mov_b32_e32 v102, v176
	v_mov_b32_e32 v103, v177
	v_mov_b32_e32 v104, v178
	v_mov_b32_e32 v105, v179
	v_lshlrev_b32_e32 v106, 16, v98
	v_and_b32_e32 v107, 0xffff0000, v98
	v_lshlrev_b32_e32 v108, 16, v102
	v_and_b32_e32 v109, 0xffff0000, v102
	v_lshlrev_b32_e32 v98, 16, v99
	v_and_b32_e32 v99, 0xffff0000, v99
	v_lshlrev_b32_e32 v102, 16, v103
	v_and_b32_e32 v103, 0xffff0000, v103
	v_pk_fma_f32 v[94:95], v[94:95], v[98:99], v[102:103]
	v_lshlrev_b32_e32 v98, 16, v100
	v_and_b32_e32 v99, 0xffff0000, v100
	v_lshlrev_b32_e32 v102, 16, v104
	v_and_b32_e32 v103, 0xffff0000, v104
	v_pk_fma_f32 v[98:99], v[88:89], v[98:99], v[102:103]
	v_lshlrev_b32_e32 v88, 16, v101
	v_and_b32_e32 v89, 0xffff0000, v101
	v_lshlrev_b32_e32 v100, 16, v105
	v_and_b32_e32 v101, 0xffff0000, v105
	v_pk_fma_f32 v[92:93], v[92:93], v[106:107], v[108:109]
	v_pk_fma_f32 v[100:101], v[90:91], v[88:89], v[100:101]
	v_cvt_pk_bf16_f32 v88, v92, v93
	v_cvt_pk_bf16_f32 v89, v94, v95
	v_cvt_pk_bf16_f32 v90, v98, v99
	v_cvt_pk_bf16_f32 v91, v100, v101
	global_store_dwordx4 v[96:97], v[88:91], off
	s_waitcnt vmcnt(5)
	s_nop 1
	v_mov_b32_e32 v88, v180
	v_mov_b32_e32 v89, v181
	v_mov_b32_e32 v90, v182
	v_mov_b32_e32 v91, v183
	s_nop 0
	v_mov_b32_e32 v92, v184
	v_mov_b32_e32 v93, v185
	v_mov_b32_e32 v94, v186
	v_mov_b32_e32 v95, v187
	v_lshlrev_b32_e32 v98, 16, v88
	v_and_b32_e32 v99, 0xffff0000, v88
	v_lshlrev_b32_e32 v100, 16, v92
	v_and_b32_e32 v101, 0xffff0000, v92
	v_lshlrev_b32_e32 v88, 16, v89
	v_and_b32_e32 v89, 0xffff0000, v89
	v_lshlrev_b32_e32 v92, 16, v93
	v_and_b32_e32 v93, 0xffff0000, v93
	v_pk_fma_f32 v[86:87], v[86:87], v[88:89], v[92:93]
	v_lshlrev_b32_e32 v88, 16, v90
	v_and_b32_e32 v89, 0xffff0000, v90
	v_lshlrev_b32_e32 v92, 16, v94
	v_and_b32_e32 v93, 0xffff0000, v94
	v_pk_fma_f32 v[88:89], v[80:81], v[88:89], v[92:93]
	v_lshlrev_b32_e32 v80, 16, v91
	v_and_b32_e32 v81, 0xffff0000, v91
	v_lshlrev_b32_e32 v90, 16, v95
	v_and_b32_e32 v91, 0xffff0000, v95
	v_pk_fma_f32 v[84:85], v[84:85], v[98:99], v[100:101]
	v_pk_fma_f32 v[90:91], v[82:83], v[80:81], v[90:91]
	v_cvt_pk_bf16_f32 v80, v84, v85
	v_cvt_pk_bf16_f32 v81, v86, v87
	v_cvt_pk_bf16_f32 v82, v88, v89
	v_cvt_pk_bf16_f32 v83, v90, v91
	global_store_dwordx4 v[96:97], v[80:83], off offset:256
	s_nop 1
	v_or_b32_e32 v80, 48, v157
	v_mad_i64_i32 v[80:81], s[2:3], v80, s80, v[140:141]
	v_lshl_add_u64 v[80:81], v[80:81], 0, s[0:1]
	v_lshl_add_u64 v[80:81], v[80:81], 0, s[68:69]
	v_lshl_add_u64 v[80:81], v[80:81], 0, v[146:147]
	s_waitcnt vmcnt(4)
	s_nop 1
	v_mov_b32_e32 v82, v188
	v_mov_b32_e32 v83, v189
	v_mov_b32_e32 v84, v190
	v_mov_b32_e32 v85, v191
	v_mov_b32_e32 v86, v192
	v_mov_b32_e32 v87, v193
	v_mov_b32_e32 v88, v194
	v_mov_b32_e32 v89, v195
	v_lshlrev_b32_e32 v90, 16, v82
	v_and_b32_e32 v91, 0xffff0000, v82
	v_lshlrev_b32_e32 v92, 16, v86
	v_and_b32_e32 v93, 0xffff0000, v86
	v_lshlrev_b32_e32 v82, 16, v83
	v_and_b32_e32 v83, 0xffff0000, v83
	v_lshlrev_b32_e32 v86, 16, v87
	v_and_b32_e32 v87, 0xffff0000, v87
	v_pk_fma_f32 v[78:79], v[78:79], v[82:83], v[86:87]
	v_lshlrev_b32_e32 v82, 16, v84
	v_and_b32_e32 v83, 0xffff0000, v84
	v_lshlrev_b32_e32 v86, 16, v88
	v_and_b32_e32 v87, 0xffff0000, v88
	v_pk_fma_f32 v[82:83], v[72:73], v[82:83], v[86:87]
	v_lshlrev_b32_e32 v72, 16, v85
	v_and_b32_e32 v73, 0xffff0000, v85
	v_lshlrev_b32_e32 v84, 16, v89
	v_and_b32_e32 v85, 0xffff0000, v89
	v_pk_fma_f32 v[76:77], v[76:77], v[90:91], v[92:93]
	v_pk_fma_f32 v[84:85], v[74:75], v[72:73], v[84:85]
	v_cvt_pk_bf16_f32 v72, v76, v77
	v_cvt_pk_bf16_f32 v73, v78, v79
	v_cvt_pk_bf16_f32 v74, v82, v83
	v_cvt_pk_bf16_f32 v75, v84, v85
	global_store_dwordx4 v[80:81], v[72:75], off
	s_waitcnt vmcnt(3)
; __device__ __forceinline__ float bflo(unsigned w) { return __uint_as_float(w << 16); }
; __device__ __forceinline__ float bfhi(unsigned w) { return __uint_as_float(w & 0xffff0000u); }
;     __device__ __forceinline__ void operator()(const f32x4 (&acc)[2][2][4][2], const Unit& u, int wr, int wc, int fr, int fq, const LAS float* rsl) const {
;     ...
;                 const int row = row0 + ai * 128 + m * 16;
; #pragma unroll
;                 for (int bj = 0; bj < 2; ++bj) {
;                     bf16_t* ptr = P + (size_t)row * PW + u.pn * 256 + bj * 128 + wc * 32 + 8 * fq;
;                     const u32x4 g = *(const u32x4*)ptr; const u32x4 t = *(const u32x4*)(ptr + 1024);
;                     f32x4 v0 = acc[ai][bj][m][0], v1 = acc[ai][bj][m][1];
;                     v0[0] = v0[0] * bflo(g.x) + bflo(t.x); v0[1] = v0[1] * bfhi(g.x) + bfhi(t.x); v0[2] = v0[2] * bflo(g.y) + bflo(t.y); v0[3] = v0[3] * bfhi(g.y) + bfhi(t.y);
;                     v1[0] = v1[0] * bflo(g.z) + bflo(t.z); v1[1] = v1[1] * bfhi(g.z) + bfhi(t.z); v1[2] = v1[2] * bflo(g.w) + bflo(t.w); v1[3] = v1[3] * bfhi(g.w) + bfhi(t.w);
;                     *(u32x4*)ptr = pack8(v0, v1);
;                 }
	s_nop 1
	v_mov_b32_e32 v72, v196
	v_mov_b32_e32 v73, v197
	v_mov_b32_e32 v74, v198
	v_mov_b32_e32 v75, v199
	s_nop 0
	v_mov_b32_e32 v76, v200
	v_mov_b32_e32 v77, v201
	v_mov_b32_e32 v78, v202
	v_mov_b32_e32 v79, v203
	v_lshlrev_b32_e32 v82, 16, v72
	v_and_b32_e32 v83, 0xffff0000, v72
	v_lshlrev_b32_e32 v84, 16, v76
	v_and_b32_e32 v85, 0xffff0000, v76
	v_lshlrev_b32_e32 v72, 16, v73
	v_and_b32_e32 v73, 0xffff0000, v73
	v_lshlrev_b32_e32 v76, 16, v77
	v_and_b32_e32 v77, 0xffff0000, v77
	v_pk_fma_f32 v[70:71], v[70:71], v[72:73], v[76:77]
	v_lshlrev_b32_e32 v72, 16, v74
	v_and_b32_e32 v73, 0xffff0000, v74
	v_lshlrev_b32_e32 v76, 16, v78
	v_and_b32_e32 v77, 0xffff0000, v78
	v_pk_fma_f32 v[72:73], v[64:65], v[72:73], v[76:77]
	v_lshlrev_b32_e32 v64, 16, v75
	v_and_b32_e32 v65, 0xffff0000, v75
	v_lshlrev_b32_e32 v74, 16, v79
	v_and_b32_e32 v75, 0xffff0000, v79
	v_pk_fma_f32 v[68:69], v[68:69], v[82:83], v[84:85]
	v_pk_fma_f32 v[74:75], v[66:67], v[64:65], v[74:75]
	v_cvt_pk_bf16_f32 v64, v68, v69
	v_cvt_pk_bf16_f32 v65, v70, v71
	v_cvt_pk_bf16_f32 v66, v72, v73
	v_cvt_pk_bf16_f32 v67, v74, v75
	global_store_dwordx4 v[80:81], v[64:67], off offset:256
	s_nop 1
	v_add_u32_e32 v64, 0x80, v157
	v_mad_i64_i32 v[64:65], s[2:3], v64, s80, v[140:141]
	v_lshl_add_u64 v[64:65], v[64:65], 0, s[0:1]
	v_lshl_add_u64 v[64:65], v[64:65], 0, s[68:69]
	v_lshl_add_u64 v[64:65], v[64:65], 0, v[146:147]
	v_mbcnt_lo_u32_b32 v67, -1, 0
	v_mbcnt_hi_u32_b32 v67, -1, v67
	v_and_b32_e32 v66, 15, v67
	v_lshrrev_b32_e32 v67, 4, v67
	v_mul_u32_u24_e32 v66, 0x1c00, v66
	v_readfirstlane_b32 s2, v64
	v_readfirstlane_b32 s3, v65
	v_lshl_or_b32 v66, v67, 4, v66
	s_nop 4
	global_load_dwordx4 v[172:175], v66, s[2:3]
	global_load_dwordx4 v[176:179], v66, s[2:3] offset:2048
	global_load_dwordx4 v[180:183], v66, s[2:3] offset:256
	global_load_dwordx4 v[184:187], v66, s[2:3] offset:2304
	s_add_u32 s2, s2, 0x1c000
	s_addc_u32 s3, s3, 0
	global_load_dwordx4 v[188:191], v66, s[2:3]
	global_load_dwordx4 v[192:195], v66, s[2:3] offset:2048
	global_load_dwordx4 v[196:199], v66, s[2:3] offset:256
	global_load_dwordx4 v[200:203], v66, s[2:3] offset:2304
	s_waitcnt vmcnt(6)
	s_nop 1
	v_mov_b32_e32 v66, v172
	v_mov_b32_e32 v67, v173
	v_mov_b32_e32 v68, v174
	v_mov_b32_e32 v69, v175
	v_mov_b32_e32 v70, v176
	v_mov_b32_e32 v71, v177
	v_mov_b32_e32 v72, v178
	v_mov_b32_e32 v73, v179
	v_lshlrev_b32_e32 v74, 16, v66
	v_and_b32_e32 v75, 0xffff0000, v66
	v_lshlrev_b32_e32 v76, 16, v70
	v_and_b32_e32 v77, 0xffff0000, v70
	v_lshlrev_b32_e32 v66, 16, v67
	v_and_b32_e32 v67, 0xffff0000, v67
	v_lshlrev_b32_e32 v70, 16, v71
	v_and_b32_e32 v71, 0xffff0000, v71
	v_pk_fma_f32 v[62:63], v[62:63], v[66:67], v[70:71]
	v_lshlrev_b32_e32 v66, 16, v68
	v_and_b32_e32 v67, 0xffff0000, v68
	v_lshlrev_b32_e32 v70, 16, v72
	v_and_b32_e32 v71, 0xffff0000, v72
	v_pk_fma_f32 v[66:67], v[56:57], v[66:67], v[70:71]
	v_lshlrev_b32_e32 v56, 16, v69
	v_and_b32_e32 v57, 0xffff0000, v69
	v_lshlrev_b32_e32 v68, 16, v73
	v_and_b32_e32 v69, 0xffff0000, v73
	v_pk_fma_f32 v[60:61], v[60:61], v[74:75], v[76:77]
	v_pk_fma_f32 v[68:69], v[58:59], v[56:57], v[68:69]
	v_cvt_pk_bf16_f32 v56, v60, v61
	v_cvt_pk_bf16_f32 v57, v62, v63
	v_cvt_pk_bf16_f32 v58, v66, v67
	v_cvt_pk_bf16_f32 v59, v68, v69
	global_store_dwordx4 v[64:65], v[56:59], off
	s_waitcnt vmcnt(5)
	s_nop 1
	v_mov_b32_e32 v56, v180
	v_mov_b32_e32 v57, v181
	v_mov_b32_e32 v58, v182
	v_mov_b32_e32 v59, v183
	s_nop 0
	v_mov_b32_e32 v60, v184
	v_mov_b32_e32 v61, v185
	v_mov_b32_e32 v62, v186
	v_mov_b32_e32 v63, v187
	v_lshlrev_b32_e32 v66, 16, v56
	v_and_b32_e32 v67, 0xffff0000, v56
	v_lshlrev_b32_e32 v68, 16, v60
	v_and_b32_e32 v69, 0xffff0000, v60
	v_lshlrev_b32_e32 v56, 16, v57
	v_and_b32_e32 v57, 0xffff0000, v57
	v_lshlrev_b32_e32 v60, 16, v61
	v_and_b32_e32 v61, 0xffff0000, v61
	v_pk_fma_f32 v[54:55], v[54:55], v[56:57], v[60:61]
	v_lshlrev_b32_e32 v56, 16, v58
	v_and_b32_e32 v57, 0xffff0000, v58
	v_lshlrev_b32_e32 v60, 16, v62
	v_and_b32_e32 v61, 0xffff0000, v62
	v_pk_fma_f32 v[56:57], v[48:49], v[56:57], v[60:61]
	v_lshlrev_b32_e32 v48, 16, v59
	v_and_b32_e32 v49, 0xffff0000, v59
	v_lshlrev_b32_e32 v58, 16, v63
	v_and_b32_e32 v59, 0xffff0000, v63
	v_pk_fma_f32 v[52:53], v[52:53], v[66:67], v[68:69]
	v_pk_fma_f32 v[58:59], v[50:51], v[48:49], v[58:59]
	v_cvt_pk_bf16_f32 v48, v52, v53
	v_cvt_pk_bf16_f32 v49, v54, v55
	v_cvt_pk_bf16_f32 v50, v56, v57
	v_cvt_pk_bf16_f32 v51, v58, v59
	global_store_dwordx4 v[64:65], v[48:51], off offset:256
	s_nop 1
	v_add_u32_e32 v48, 0x90, v157
	v_mad_i64_i32 v[48:49], s[2:3], v48, s80, v[140:141]
	v_lshl_add_u64 v[48:49], v[48:49], 0, s[0:1]
	v_lshl_add_u64 v[48:49], v[48:49], 0, s[68:69]
	v_lshl_add_u64 v[48:49], v[48:49], 0, v[146:147]
	s_waitcnt vmcnt(4)
	s_nop 1
	v_mov_b32_e32 v50, v188
	v_mov_b32_e32 v51, v189
	v_mov_b32_e32 v52, v190
	v_mov_b32_e32 v53, v191
	v_mov_b32_e32 v54, v192
	v_mov_b32_e32 v55, v193
	v_mov_b32_e32 v56, v194
	v_mov_b32_e32 v57, v195
	v_lshlrev_b32_e32 v58, 16, v50
	v_and_b32_e32 v59, 0xffff0000, v50
	v_lshlrev_b32_e32 v60, 16, v54
	v_and_b32_e32 v61, 0xffff0000, v54
	v_lshlrev_b32_e32 v50, 16, v51
	v_and_b32_e32 v51, 0xffff0000, v51
	v_lshlrev_b32_e32 v54, 16, v55
	v_and_b32_e32 v55, 0xffff0000, v55
	v_pk_fma_f32 v[46:47], v[46:47], v[50:51], v[54:55]
	v_lshlrev_b32_e32 v50, 16, v52
	v_and_b32_e32 v51, 0xffff0000, v52
	v_lshlrev_b32_e32 v54, 16, v56
	v_and_b32_e32 v55, 0xffff0000, v56
	v_pk_fma_f32 v[50:51], v[40:41], v[50:51], v[54:55]
	v_lshlrev_b32_e32 v40, 16, v53
	v_and_b32_e32 v41, 0xffff0000, v53
	v_lshlrev_b32_e32 v52, 16, v57
	v_and_b32_e32 v53, 0xffff0000, v57
	v_pk_fma_f32 v[44:45], v[44:45], v[58:59], v[60:61]
	v_pk_fma_f32 v[52:53], v[42:43], v[40:41], v[52:53]
	v_cvt_pk_bf16_f32 v40, v44, v45
	v_cvt_pk_bf16_f32 v41, v46, v47
	v_cvt_pk_bf16_f32 v42, v50, v51
	v_cvt_pk_bf16_f32 v43, v52, v53
	global_store_dwordx4 v[48:49], v[40:43], off
	s_waitcnt vmcnt(3)
; __device__ __forceinline__ float bflo(unsigned w) { return __uint_as_float(w << 16); }
; __device__ __forceinline__ float bfhi(unsigned w) { return __uint_as_float(w & 0xffff0000u); }
;     __device__ __forceinline__ void operator()(const f32x4 (&acc)[2][2][4][2], const Unit& u, int wr, int wc, int fr, int fq, const LAS float* rsl) const {
;     ...
;                 const int row = row0 + ai * 128 + m * 16;
; #pragma unroll
;                 for (int bj = 0; bj < 2; ++bj) {
;                     bf16_t* ptr = P + (size_t)row * PW + u.pn * 256 + bj * 128 + wc * 32 + 8 * fq;
;                     const u32x4 g = *(const u32x4*)ptr; const u32x4 t = *(const u32x4*)(ptr + 1024);
;                     f32x4 v0 = acc[ai][bj][m][0], v1 = acc[ai][bj][m][1];
;                     v0[0] = v0[0] * bflo(g.x) + bflo(t.x); v0[1] = v0[1] * bfhi(g.x) + bfhi(t.x); v0[2] = v0[2] * bflo(g.y) + bflo(t.y); v0[3] = v0[3] * bfhi(g.y) + bfhi(t.y);
;                     v1[0] = v1[0] * bflo(g.z) + bflo(t.z); v1[1] = v1[1] * bfhi(g.z) + bfhi(t.z); v1[2] = v1[2] * bflo(g.w) + bflo(t.w); v1[3] = v1[3] * bfhi(g.w) + bfhi(t.w);
;                     *(u32x4*)ptr = pack8(v0, v1);
;                 }
	s_nop 1
	v_mov_b32_e32 v40, v196
	v_mov_b32_e32 v41, v197
	v_mov_b32_e32 v42, v198
	v_mov_b32_e32 v43, v199
	s_nop 0
	v_mov_b32_e32 v44, v200
	v_mov_b32_e32 v45, v201
	v_mov_b32_e32 v46, v202
	v_mov_b32_e32 v47, v203
	v_lshlrev_b32_e32 v50, 16, v40
	v_and_b32_e32 v51, 0xffff0000, v40
	v_lshlrev_b32_e32 v52, 16, v44
	v_and_b32_e32 v53, 0xffff0000, v44
	v_lshlrev_b32_e32 v40, 16, v41
	v_and_b32_e32 v41, 0xffff0000, v41
	v_lshlrev_b32_e32 v44, 16, v45
	v_and_b32_e32 v45, 0xffff0000, v45
	v_pk_fma_f32 v[38:39], v[38:39], v[40:41], v[44:45]
	v_lshlrev_b32_e32 v40, 16, v42
	v_and_b32_e32 v41, 0xffff0000, v42
	v_lshlrev_b32_e32 v44, 16, v46
	v_and_b32_e32 v45, 0xffff0000, v46
	v_pk_fma_f32 v[40:41], v[32:33], v[40:41], v[44:45]
	v_lshlrev_b32_e32 v32, 16, v43
	v_and_b32_e32 v33, 0xffff0000, v43
	v_lshlrev_b32_e32 v42, 16, v47
	v_and_b32_e32 v43, 0xffff0000, v47
	v_pk_fma_f32 v[36:37], v[36:37], v[50:51], v[52:53]
	v_pk_fma_f32 v[42:43], v[34:35], v[32:33], v[42:43]
	v_cvt_pk_bf16_f32 v32, v36, v37
	v_cvt_pk_bf16_f32 v33, v38, v39
	v_cvt_pk_bf16_f32 v34, v40, v41
	v_cvt_pk_bf16_f32 v35, v42, v43
	global_store_dwordx4 v[48:49], v[32:35], off offset:256
	s_nop 1
	v_add_u32_e32 v32, 0xa0, v157
	v_mad_i64_i32 v[32:33], s[2:3], v32, s80, v[140:141]
	v_lshl_add_u64 v[32:33], v[32:33], 0, s[0:1]
	v_lshl_add_u64 v[32:33], v[32:33], 0, s[68:69]
	v_lshl_add_u64 v[32:33], v[32:33], 0, v[146:147]
	v_mbcnt_lo_u32_b32 v35, -1, 0
	v_mbcnt_hi_u32_b32 v35, -1, v35
	v_and_b32_e32 v34, 15, v35
	v_lshrrev_b32_e32 v35, 4, v35
	v_mul_u32_u24_e32 v34, 0x1c00, v34
	v_readfirstlane_b32 s2, v32
	v_readfirstlane_b32 s3, v33
	v_lshl_or_b32 v34, v35, 4, v34
	s_nop 4
	global_load_dwordx4 v[172:175], v34, s[2:3]
	global_load_dwordx4 v[176:179], v34, s[2:3] offset:2048
	global_load_dwordx4 v[180:183], v34, s[2:3] offset:256
	global_load_dwordx4 v[184:187], v34, s[2:3] offset:2304
	s_add_u32 s2, s2, 0x1c000
	s_addc_u32 s3, s3, 0
	global_load_dwordx4 v[188:191], v34, s[2:3]
	global_load_dwordx4 v[192:195], v34, s[2:3] offset:2048
	global_load_dwordx4 v[196:199], v34, s[2:3] offset:256
	global_load_dwordx4 v[200:203], v34, s[2:3] offset:2304
	s_waitcnt vmcnt(6)
	s_nop 1
	v_mov_b32_e32 v34, v172
	v_mov_b32_e32 v35, v173
	v_mov_b32_e32 v36, v174
	v_mov_b32_e32 v37, v175
	v_mov_b32_e32 v38, v176
	v_mov_b32_e32 v39, v177
	v_mov_b32_e32 v40, v178
	v_mov_b32_e32 v41, v179
	v_lshlrev_b32_e32 v42, 16, v34
	v_and_b32_e32 v43, 0xffff0000, v34
	v_lshlrev_b32_e32 v44, 16, v38
	v_and_b32_e32 v45, 0xffff0000, v38
	v_lshlrev_b32_e32 v34, 16, v35
	v_and_b32_e32 v35, 0xffff0000, v35
	v_lshlrev_b32_e32 v38, 16, v39
	v_and_b32_e32 v39, 0xffff0000, v39
	v_pk_fma_f32 v[30:31], v[30:31], v[34:35], v[38:39]
	v_lshlrev_b32_e32 v34, 16, v36
	v_and_b32_e32 v35, 0xffff0000, v36
	v_lshlrev_b32_e32 v38, 16, v40
	v_and_b32_e32 v39, 0xffff0000, v40
	v_pk_fma_f32 v[34:35], v[24:25], v[34:35], v[38:39]
	v_lshlrev_b32_e32 v24, 16, v37
	v_and_b32_e32 v25, 0xffff0000, v37
	v_lshlrev_b32_e32 v36, 16, v41
	v_and_b32_e32 v37, 0xffff0000, v41
	v_pk_fma_f32 v[28:29], v[28:29], v[42:43], v[44:45]
	v_pk_fma_f32 v[36:37], v[26:27], v[24:25], v[36:37]
	v_cvt_pk_bf16_f32 v24, v28, v29
	v_cvt_pk_bf16_f32 v25, v30, v31
	v_cvt_pk_bf16_f32 v26, v34, v35
	v_cvt_pk_bf16_f32 v27, v36, v37
	global_store_dwordx4 v[32:33], v[24:27], off
	s_waitcnt vmcnt(5)
; __device__ __forceinline__ float bflo(unsigned w) { return __uint_as_float(w << 16); }
; __device__ __forceinline__ float bfhi(unsigned w) { return __uint_as_float(w & 0xffff0000u); }
; #define PG8_BAR __builtin_amdgcn_s_barrier()
;     ...
;         if (!has_next) break;
; #pragma unroll
;         for (int a = 0; a < 2; ++a)
; #pragma unroll
;             for (int b = 0; b < 2; ++b)
; #pragma unroll
;                 for (int m = 0; m < 4; ++m)
; #pragma unroll
;                     for (int n = 0; n < 2; ++n) acc[a][b][m][n] = (f32x4){0.f, 0.f, 0.f, 0.f};
;         cur = nxt; cA = nA; cB = nB; ++ui;
;         if constexpr (ALIGN_EPI) { if (wr == 1) PG8_BAR; }
;     __device__ __forceinline__ void operator()(const f32x4 (&acc)[2][2][4][2], const Unit& u, int wr, int wc, int fr, int fq, const LAS float* rsl) const {
;     ...
;                 const int row = row0 + ai * 128 + m * 16;
; #pragma unroll
;                 for (int bj = 0; bj < 2; ++bj) {
;                     bf16_t* ptr = P + (size_t)row * PW + u.pn * 256 + bj * 128 + wc * 32 + 8 * fq;
;                     const u32x4 g = *(const u32x4*)ptr; const u32x4 t = *(const u32x4*)(ptr + 1024);
;                     f32x4 v0 = acc[ai][bj][m][0], v1 = acc[ai][bj][m][1];
;                     v0[0] = v0[0] * bflo(g.x) + bflo(t.x); v0[1] = v0[1] * bfhi(g.x) + bfhi(t.x); v0[2] = v0[2] * bflo(g.y) + bflo(t.y); v0[3] = v0[3] * bfhi(g.y) + bfhi(t.y);
;                     v1[0] = v1[0] * bflo(g.z) + bflo(t.z); v1[1] = v1[1] * bfhi(g.z) + bfhi(t.z); v1[2] = v1[2] * bflo(g.w) + bflo(t.w); v1[3] = v1[3] * bfhi(g.w) + bfhi(t.w);
;                     *(u32x4*)ptr = pack8(v0, v1);
;                 }
;                 asm volatile("" ::: "memory");
	s_nop 1
	v_mov_b32_e32 v24, v180
	v_mov_b32_e32 v25, v181
	v_mov_b32_e32 v26, v182
	v_mov_b32_e32 v27, v183
	s_nop 0
	v_mov_b32_e32 v28, v184
	v_mov_b32_e32 v29, v185
	v_mov_b32_e32 v30, v186
	v_mov_b32_e32 v31, v187
	v_lshlrev_b32_e32 v34, 16, v24
	v_and_b32_e32 v35, 0xffff0000, v24
	v_lshlrev_b32_e32 v36, 16, v28
	v_and_b32_e32 v37, 0xffff0000, v28
	v_lshlrev_b32_e32 v24, 16, v25
	v_and_b32_e32 v25, 0xffff0000, v25
	v_lshlrev_b32_e32 v28, 16, v29
	v_and_b32_e32 v29, 0xffff0000, v29
	v_pk_fma_f32 v[22:23], v[22:23], v[24:25], v[28:29]
	v_lshlrev_b32_e32 v24, 16, v26
	v_and_b32_e32 v25, 0xffff0000, v26
	v_lshlrev_b32_e32 v28, 16, v30
	v_and_b32_e32 v29, 0xffff0000, v30
	v_pk_fma_f32 v[24:25], v[16:17], v[24:25], v[28:29]
	v_lshlrev_b32_e32 v16, 16, v27
	v_and_b32_e32 v17, 0xffff0000, v27
	v_lshlrev_b32_e32 v26, 16, v31
	v_and_b32_e32 v27, 0xffff0000, v31
	v_pk_fma_f32 v[20:21], v[20:21], v[34:35], v[36:37]
	v_pk_fma_f32 v[26:27], v[18:19], v[16:17], v[26:27]
	v_cvt_pk_bf16_f32 v16, v20, v21
	v_cvt_pk_bf16_f32 v17, v22, v23
	v_cvt_pk_bf16_f32 v18, v24, v25
	v_cvt_pk_bf16_f32 v19, v26, v27
	global_store_dwordx4 v[32:33], v[16:19], off offset:256
	s_nop 1
	v_add_u32_e32 v16, 0xb0, v157
	v_mad_i64_i32 v[16:17], s[2:3], v16, s80, v[140:141]
	v_lshl_add_u64 v[16:17], v[16:17], 0, s[0:1]
	v_lshl_add_u64 v[16:17], v[16:17], 0, s[68:69]
	v_lshl_add_u64 v[16:17], v[16:17], 0, v[146:147]
	s_waitcnt vmcnt(4)
	s_nop 1
	v_mov_b32_e32 v18, v188
	v_mov_b32_e32 v19, v189
	v_mov_b32_e32 v20, v190
	v_mov_b32_e32 v21, v191
	v_mov_b32_e32 v22, v192
	v_mov_b32_e32 v23, v193
	v_mov_b32_e32 v24, v194
	v_mov_b32_e32 v25, v195
	s_mov_b64 s[0:1], -1
	v_lshlrev_b32_e32 v26, 16, v18
	v_and_b32_e32 v27, 0xffff0000, v18
	v_lshlrev_b32_e32 v28, 16, v22
	v_and_b32_e32 v29, 0xffff0000, v22
	v_lshlrev_b32_e32 v18, 16, v19
	v_and_b32_e32 v19, 0xffff0000, v19
	v_lshlrev_b32_e32 v22, 16, v23
	v_and_b32_e32 v23, 0xffff0000, v23
	v_pk_fma_f32 v[14:15], v[14:15], v[18:19], v[22:23]
	v_lshlrev_b32_e32 v18, 16, v20
	v_and_b32_e32 v19, 0xffff0000, v20
	v_lshlrev_b32_e32 v22, 16, v24
	v_and_b32_e32 v23, 0xffff0000, v24
	v_pk_fma_f32 v[18:19], v[8:9], v[18:19], v[22:23]
	v_lshlrev_b32_e32 v8, 16, v21
	v_and_b32_e32 v9, 0xffff0000, v21
	v_lshlrev_b32_e32 v20, 16, v25
	v_and_b32_e32 v21, 0xffff0000, v25
	v_pk_fma_f32 v[12:13], v[12:13], v[26:27], v[28:29]
	v_pk_fma_f32 v[20:21], v[10:11], v[8:9], v[20:21]
	v_cvt_pk_bf16_f32 v8, v12, v13
	v_cvt_pk_bf16_f32 v9, v14, v15
	v_cvt_pk_bf16_f32 v10, v18, v19
	v_cvt_pk_bf16_f32 v11, v20, v21
	global_store_dwordx4 v[16:17], v[8:11], off
	s_waitcnt vmcnt(3)
	s_nop 1
	v_mov_b32_e32 v8, v196
	v_mov_b32_e32 v9, v197
	v_mov_b32_e32 v10, v198
	v_mov_b32_e32 v11, v199
	s_nop 0
	v_mov_b32_e32 v12, v200
	v_mov_b32_e32 v13, v201
	v_mov_b32_e32 v14, v202
	v_mov_b32_e32 v15, v203
	v_lshlrev_b32_e32 v18, 16, v8
	v_and_b32_e32 v19, 0xffff0000, v8
	v_lshlrev_b32_e32 v20, 16, v12
	v_and_b32_e32 v21, 0xffff0000, v12
	v_lshlrev_b32_e32 v8, 16, v9
	v_and_b32_e32 v9, 0xffff0000, v9
	v_lshlrev_b32_e32 v12, 16, v13
	v_and_b32_e32 v13, 0xffff0000, v13
	v_pk_fma_f32 v[6:7], v[6:7], v[8:9], v[12:13]
	v_lshlrev_b32_e32 v8, 16, v10
	v_and_b32_e32 v9, 0xffff0000, v10
	v_lshlrev_b32_e32 v12, 16, v14
	v_and_b32_e32 v13, 0xffff0000, v14
	v_pk_fma_f32 v[8:9], v[0:1], v[8:9], v[12:13]
	v_lshlrev_b32_e32 v0, 16, v11
	v_and_b32_e32 v1, 0xffff0000, v11
	v_lshlrev_b32_e32 v10, 16, v15
	v_and_b32_e32 v11, 0xffff0000, v15
	v_pk_fma_f32 v[4:5], v[4:5], v[18:19], v[20:21]
	v_pk_fma_f32 v[10:11], v[2:3], v[0:1], v[10:11]
	v_cvt_pk_bf16_f32 v0, v4, v5
	v_cvt_pk_bf16_f32 v1, v6, v7
	v_cvt_pk_bf16_f32 v2, v8, v9
	v_cvt_pk_bf16_f32 v3, v10, v11
	global_store_dwordx4 v[16:17], v[0:3], off offset:256
	s_cbranch_vccnz .LBB0_301
	s_andn2_b64 vcc, exec, s[18:19]
	s_cbranch_vccnz .LBB0_300
	s_barrier
	s_branch .LBB0_300
